# instruction selection: accumulator zeroing between GEMM units as 63 v_mov_b64 instead of 126 v_mov_b32 per unit; on top of v45
# speedup vs baseline: 1.0040x; 1.0040x over previous
; template <class Desc, class Epi>
; DI void gemm_phase(LAS unsigned char* lds, const Desc& D, const Epi& E, int wv) {
;     ...
; #pragma unroll
;         for (int a = 0; a < 2; ++a)
; #pragma unroll
;             for (int b = 0; b < 2; ++b)
; #pragma unroll
;                 for (int m = 0; m < 4; ++m)
; #pragma unroll
;                     for (int n = 0; n < 2; ++n) acc[a][b][m][n] = (f32x4){0.f, 0.f, 0.f, 0.f};
;         cur = nxt; cA = nA; cB = nB; ++ui;
.LBB0_291:
	s_add_u32 s64, s64, 0x80080
	s_addc_u32 s65, s65, 0
	s_add_u32 s53, s66, 0x100
	v_mov_b32_e32 v0, 0
	s_addc_u32 s61, s67, 0
	s_mov_b32 s63, -2
	v_mov_b32_e32 v1, v0
	v_mov_b64_e32 v[2:3], 0
	v_mov_b64_e32 v[4:5], 0
	v_mov_b64_e32 v[6:7], 0
	v_mov_b64_e32 v[16:17], 0
	v_mov_b64_e32 v[18:19], 0
	v_mov_b64_e32 v[20:21], 0
	v_mov_b64_e32 v[22:23], 0
	v_mov_b64_e32 v[32:33], 0
	v_mov_b64_e32 v[34:35], 0
	v_mov_b64_e32 v[36:37], 0
	v_mov_b64_e32 v[38:39], 0
	v_mov_b64_e32 v[48:49], 0
	v_mov_b64_e32 v[50:51], 0
	v_mov_b64_e32 v[52:53], 0
	v_mov_b64_e32 v[54:55], 0
	v_mov_b64_e32 v[8:9], 0
	v_mov_b64_e32 v[10:11], 0
	v_mov_b64_e32 v[12:13], 0
	v_mov_b64_e32 v[14:15], 0
	v_mov_b64_e32 v[24:25], 0
	v_mov_b64_e32 v[26:27], 0
	v_mov_b64_e32 v[28:29], 0
	v_mov_b64_e32 v[30:31], 0
	v_mov_b64_e32 v[40:41], 0
	v_mov_b64_e32 v[42:43], 0
	v_mov_b64_e32 v[44:45], 0
	v_mov_b64_e32 v[46:47], 0
	v_mov_b64_e32 v[56:57], 0
	v_mov_b64_e32 v[58:59], 0
	v_mov_b64_e32 v[60:61], 0
	v_mov_b64_e32 v[62:63], 0
	v_mov_b64_e32 v[64:65], 0
	v_mov_b64_e32 v[66:67], 0
	v_mov_b64_e32 v[68:69], 0
	v_mov_b64_e32 v[70:71], 0
	v_mov_b64_e32 v[80:81], 0
	v_mov_b64_e32 v[82:83], 0
	v_mov_b64_e32 v[84:85], 0
	v_mov_b64_e32 v[86:87], 0
	v_mov_b64_e32 v[96:97], 0
	v_mov_b64_e32 v[98:99], 0
	v_mov_b64_e32 v[100:101], 0
	v_mov_b64_e32 v[102:103], 0
	v_mov_b64_e32 v[112:113], 0
	v_mov_b64_e32 v[114:115], 0
	v_mov_b64_e32 v[116:117], 0
	v_mov_b64_e32 v[118:119], 0
	v_mov_b64_e32 v[72:73], 0
	v_mov_b64_e32 v[74:75], 0
	v_mov_b64_e32 v[76:77], 0
	v_mov_b64_e32 v[78:79], 0
	v_mov_b64_e32 v[88:89], 0
	v_mov_b64_e32 v[90:91], 0
	v_mov_b64_e32 v[92:93], 0
	v_mov_b64_e32 v[94:95], 0
	v_mov_b64_e32 v[104:105], 0
	v_mov_b64_e32 v[106:107], 0
	v_mov_b64_e32 v[108:109], 0
	v_mov_b64_e32 v[110:111], 0
	v_mov_b64_e32 v[120:121], 0
	v_mov_b64_e32 v[122:123], 0
	v_mov_b64_e32 v[124:125], 0
	v_mov_b64_e32 v[126:127], 0

; template <class Desc, class Epi>
; DI void gemm_phase(LAS unsigned char* lds, const Desc& D, const Epi& E, int wv) {
;     ...
; #pragma unroll
;         for (int a = 0; a < 2; ++a)
; #pragma unroll
;             for (int b = 0; b < 2; ++b)
; #pragma unroll
;                 for (int m = 0; m < 4; ++m)
; #pragma unroll
;                     for (int n = 0; n < 2; ++n) acc[a][b][m][n] = (f32x4){0.f, 0.f, 0.f, 0.f};
;         cur = nxt; cA = nA; cB = nB; ++ui;
.LBB0_338:
	s_add_u32 s6, s6, 0x20080
	s_addc_u32 s7, s7, 0
	s_add_u32 s53, s8, 0x100
	v_mov_b32_e32 v0, 0
	s_addc_u32 s66, s9, 0
	s_mov_b32 s67, -2
	v_mov_b32_e32 v1, v0
	v_mov_b64_e32 v[2:3], 0
	v_mov_b64_e32 v[4:5], 0
	v_mov_b64_e32 v[6:7], 0
	v_mov_b64_e32 v[16:17], 0
	v_mov_b64_e32 v[18:19], 0
	v_mov_b64_e32 v[20:21], 0
	v_mov_b64_e32 v[22:23], 0
	v_mov_b64_e32 v[32:33], 0
	v_mov_b64_e32 v[34:35], 0
	v_mov_b64_e32 v[36:37], 0
	v_mov_b64_e32 v[38:39], 0
	v_mov_b64_e32 v[48:49], 0
	v_mov_b64_e32 v[50:51], 0
	v_mov_b64_e32 v[52:53], 0
	v_mov_b64_e32 v[54:55], 0
	v_mov_b64_e32 v[8:9], 0
	v_mov_b64_e32 v[10:11], 0
	v_mov_b64_e32 v[12:13], 0
	v_mov_b64_e32 v[14:15], 0
	v_mov_b64_e32 v[24:25], 0
	v_mov_b64_e32 v[26:27], 0
	v_mov_b64_e32 v[28:29], 0
	v_mov_b64_e32 v[30:31], 0
	v_mov_b64_e32 v[40:41], 0
	v_mov_b64_e32 v[42:43], 0
	v_mov_b64_e32 v[44:45], 0
	v_mov_b64_e32 v[46:47], 0
	v_mov_b64_e32 v[56:57], 0
	v_mov_b64_e32 v[58:59], 0
	v_mov_b64_e32 v[60:61], 0
	v_mov_b64_e32 v[62:63], 0
	v_mov_b64_e32 v[64:65], 0
	v_mov_b64_e32 v[66:67], 0
	v_mov_b64_e32 v[68:69], 0
	v_mov_b64_e32 v[70:71], 0
	v_mov_b64_e32 v[80:81], 0
	v_mov_b64_e32 v[82:83], 0
	v_mov_b64_e32 v[84:85], 0
	v_mov_b64_e32 v[86:87], 0
	v_mov_b64_e32 v[96:97], 0
	v_mov_b64_e32 v[98:99], 0
	v_mov_b64_e32 v[100:101], 0
	v_mov_b64_e32 v[102:103], 0
	v_mov_b64_e32 v[112:113], 0
	v_mov_b64_e32 v[114:115], 0
	v_mov_b64_e32 v[116:117], 0
	v_mov_b64_e32 v[118:119], 0
	v_mov_b64_e32 v[72:73], 0
	v_mov_b64_e32 v[74:75], 0
	v_mov_b64_e32 v[76:77], 0
	v_mov_b64_e32 v[78:79], 0
	v_mov_b64_e32 v[88:89], 0
	v_mov_b64_e32 v[90:91], 0
	v_mov_b64_e32 v[92:93], 0
	v_mov_b64_e32 v[94:95], 0
	v_mov_b64_e32 v[104:105], 0
	v_mov_b64_e32 v[106:107], 0
	v_mov_b64_e32 v[108:109], 0
	v_mov_b64_e32 v[110:111], 0
	v_mov_b64_e32 v[120:121], 0
	v_mov_b64_e32 v[122:123], 0
	v_mov_b64_e32 v[124:125], 0
	v_mov_b64_e32 v[126:127], 0

; template <class Desc, class Epi>
; DI void gemm_phase(LAS unsigned char* lds, const Desc& D, const Epi& E, int wv) {
;     ...
; #pragma unroll
;         for (int a = 0; a < 2; ++a)
; #pragma unroll
;             for (int b = 0; b < 2; ++b)
; #pragma unroll
;                 for (int m = 0; m < 4; ++m)
; #pragma unroll
;                     for (int n = 0; n < 2; ++n) acc[a][b][m][n] = (f32x4){0.f, 0.f, 0.f, 0.f};
;         cur = nxt; cA = nA; cB = nB; ++ui;
.LBB0_580:
	s_add_u32 s66, s66, 0x100080
	s_addc_u32 s67, s67, 0
	s_add_u32 s1, s68, 0x100
	v_mov_b32_e32 v0, 0
	s_addc_u32 s47, s69, 0
	s_mov_b32 s48, -2
	v_mov_b32_e32 v1, v0
	v_mov_b64_e32 v[2:3], 0
	v_mov_b64_e32 v[4:5], 0
	v_mov_b64_e32 v[6:7], 0
	v_mov_b64_e32 v[16:17], 0
	v_mov_b64_e32 v[18:19], 0
	v_mov_b64_e32 v[20:21], 0
	v_mov_b64_e32 v[22:23], 0
	v_mov_b64_e32 v[32:33], 0
	v_mov_b64_e32 v[34:35], 0
	v_mov_b64_e32 v[36:37], 0
	v_mov_b64_e32 v[38:39], 0
	v_mov_b64_e32 v[48:49], 0
	v_mov_b64_e32 v[50:51], 0
	v_mov_b64_e32 v[52:53], 0
	v_mov_b64_e32 v[54:55], 0
	v_mov_b64_e32 v[8:9], 0
	v_mov_b64_e32 v[10:11], 0
	v_mov_b64_e32 v[12:13], 0
	v_mov_b64_e32 v[14:15], 0
	v_mov_b64_e32 v[24:25], 0
	v_mov_b64_e32 v[26:27], 0
	v_mov_b64_e32 v[28:29], 0
	v_mov_b64_e32 v[30:31], 0
	v_mov_b64_e32 v[40:41], 0
	v_mov_b64_e32 v[42:43], 0
	v_mov_b64_e32 v[44:45], 0
	v_mov_b64_e32 v[46:47], 0
	v_mov_b64_e32 v[56:57], 0
	v_mov_b64_e32 v[58:59], 0
	v_mov_b64_e32 v[60:61], 0
	v_mov_b64_e32 v[62:63], 0
	v_mov_b64_e32 v[64:65], 0
	v_mov_b64_e32 v[66:67], 0
	v_mov_b64_e32 v[68:69], 0
	v_mov_b64_e32 v[70:71], 0
	v_mov_b64_e32 v[80:81], 0
	v_mov_b64_e32 v[82:83], 0
	v_mov_b64_e32 v[84:85], 0
	v_mov_b64_e32 v[86:87], 0
	v_mov_b64_e32 v[96:97], 0
	v_mov_b64_e32 v[98:99], 0
	v_mov_b64_e32 v[100:101], 0
	v_mov_b64_e32 v[102:103], 0
	v_mov_b64_e32 v[112:113], 0
	v_mov_b64_e32 v[114:115], 0
	v_mov_b64_e32 v[116:117], 0
	v_mov_b64_e32 v[118:119], 0
	v_mov_b64_e32 v[72:73], 0
	v_mov_b64_e32 v[74:75], 0
	v_mov_b64_e32 v[76:77], 0
	v_mov_b64_e32 v[78:79], 0
	v_mov_b64_e32 v[88:89], 0
	v_mov_b64_e32 v[90:91], 0
	v_mov_b64_e32 v[92:93], 0
	v_mov_b64_e32 v[94:95], 0
	v_mov_b64_e32 v[104:105], 0
	v_mov_b64_e32 v[106:107], 0
	v_mov_b64_e32 v[108:109], 0
	v_mov_b64_e32 v[110:111], 0
	v_mov_b64_e32 v[120:121], 0
	v_mov_b64_e32 v[122:123], 0
	v_mov_b64_e32 v[124:125], 0
	v_mov_b64_e32 v[126:127], 0

; template <class Desc, class Epi>
; DI void gemm_phase(LAS unsigned char* lds, const Desc& D, const Epi& E, int wv) {
;     ...
; #pragma unroll
;         for (int a = 0; a < 2; ++a)
; #pragma unroll
;             for (int b = 0; b < 2; ++b)
; #pragma unroll
;                 for (int m = 0; m < 4; ++m)
; #pragma unroll
;                     for (int n = 0; n < 2; ++n) acc[a][b][m][n] = (f32x4){0.f, 0.f, 0.f, 0.f};
;         cur = nxt; cA = nA; cB = nB; ++ui;
.LBB0_762:
	s_add_u32 s21, s62, 0x100
	v_mov_b32_e32 v0, 0
	s_addc_u32 s23, s63, 0
	s_mov_b32 s49, -2
	s_mov_b64 s[62:63], 0
	v_mov_b32_e32 v1, v0
	v_mov_b64_e32 v[2:3], 0
	v_mov_b64_e32 v[4:5], 0
	v_mov_b64_e32 v[6:7], 0
	v_mov_b64_e32 v[16:17], 0
	v_mov_b64_e32 v[18:19], 0
	v_mov_b64_e32 v[20:21], 0
	v_mov_b64_e32 v[22:23], 0
	v_mov_b64_e32 v[32:33], 0
	v_mov_b64_e32 v[34:35], 0
	v_mov_b64_e32 v[36:37], 0
	v_mov_b64_e32 v[38:39], 0
	v_mov_b64_e32 v[48:49], 0
	v_mov_b64_e32 v[50:51], 0
	v_mov_b64_e32 v[52:53], 0
	v_mov_b64_e32 v[54:55], 0
	v_mov_b64_e32 v[8:9], 0
	v_mov_b64_e32 v[10:11], 0
	v_mov_b64_e32 v[12:13], 0
	s_waitcnt vmcnt(0)
	v_mov_b64_e32 v[14:15], 0
	v_mov_b64_e32 v[24:25], 0
	v_mov_b64_e32 v[26:27], 0
	v_mov_b64_e32 v[28:29], 0
	v_mov_b64_e32 v[30:31], 0
	v_mov_b64_e32 v[40:41], 0
	v_mov_b64_e32 v[42:43], 0
	v_mov_b64_e32 v[44:45], 0
	v_mov_b64_e32 v[46:47], 0
	v_mov_b64_e32 v[56:57], 0
	v_mov_b64_e32 v[58:59], 0
	v_mov_b64_e32 v[60:61], 0
	v_mov_b64_e32 v[62:63], 0
	v_mov_b64_e32 v[64:65], 0
	v_mov_b64_e32 v[66:67], 0
	v_mov_b64_e32 v[68:69], 0
	v_mov_b64_e32 v[70:71], 0
	v_mov_b64_e32 v[80:81], 0
	v_mov_b64_e32 v[82:83], 0
	v_mov_b64_e32 v[84:85], 0
	v_mov_b64_e32 v[86:87], 0
	v_mov_b64_e32 v[96:97], 0
	v_mov_b64_e32 v[98:99], 0
	v_mov_b64_e32 v[100:101], 0
	v_mov_b64_e32 v[102:103], 0
	v_mov_b64_e32 v[112:113], 0
	v_mov_b64_e32 v[114:115], 0
	v_mov_b64_e32 v[116:117], 0
	v_mov_b64_e32 v[118:119], 0
	v_mov_b64_e32 v[72:73], 0
	v_mov_b64_e32 v[74:75], 0
	v_mov_b64_e32 v[76:77], 0
	v_mov_b64_e32 v[78:79], 0
	v_mov_b64_e32 v[88:89], 0
	v_mov_b64_e32 v[90:91], 0
	v_mov_b64_e32 v[92:93], 0
	v_mov_b64_e32 v[94:95], 0
	v_mov_b64_e32 v[104:105], 0
	v_mov_b64_e32 v[106:107], 0
	v_mov_b64_e32 v[108:109], 0
	v_mov_b64_e32 v[110:111], 0
	v_mov_b64_e32 v[120:121], 0
	v_mov_b64_e32 v[122:123], 0
	v_mov_b64_e32 v[124:125], 0
	v_mov_b64_e32 v[126:127], 0

; template <class Desc, class Epi>
; DI void gemm_phase(LAS unsigned char* lds, const Desc& D, const Epi& E, int wv) {
;     ...
; #pragma unroll
;         for (int a = 0; a < 2; ++a)
; #pragma unroll
;             for (int b = 0; b < 2; ++b)
; #pragma unroll
;                 for (int m = 0; m < 4; ++m)
; #pragma unroll
;                     for (int n = 0; n < 2; ++n) acc[a][b][m][n] = (f32x4){0.f, 0.f, 0.f, 0.f};
;         cur = nxt; cA = nA; cB = nB; ++ui;
.LBB0_830:
	s_add_u32 s6, s6, 0x80080
	s_addc_u32 s7, s7, 0
	s_add_u32 s23, s66, 0x100
	v_mov_b32_e32 v0, 0
	s_addc_u32 s49, s67, 0
	s_mov_b32 s50, -2
	v_mov_b32_e32 v1, v0
	v_mov_b64_e32 v[2:3], 0
	v_mov_b64_e32 v[4:5], 0
	v_mov_b64_e32 v[6:7], 0
	v_mov_b64_e32 v[8:9], 0
	v_mov_b64_e32 v[10:11], 0
	v_mov_b64_e32 v[16:17], 0
	v_mov_b64_e32 v[18:19], 0
	v_mov_b64_e32 v[24:25], 0
	v_mov_b64_e32 v[26:27], 0
	v_mov_b64_e32 v[32:33], 0
	v_mov_b64_e32 v[34:35], 0
	v_mov_b64_e32 v[40:41], 0
	v_mov_b64_e32 v[42:43], 0
	v_mov_b64_e32 v[48:49], 0
	v_mov_b64_e32 v[50:51], 0
	v_mov_b64_e32 v[12:13], 0
	v_mov_b64_e32 v[14:15], 0
	v_mov_b64_e32 v[20:21], 0
	v_mov_b64_e32 v[22:23], 0
	v_mov_b64_e32 v[28:29], 0
	v_mov_b64_e32 v[30:31], 0
	v_mov_b64_e32 v[36:37], 0
	v_mov_b64_e32 v[38:39], 0
	v_mov_b64_e32 v[44:45], 0
	v_mov_b64_e32 v[46:47], 0
	v_mov_b64_e32 v[52:53], 0
	v_mov_b64_e32 v[54:55], 0
	v_mov_b64_e32 v[56:57], 0
	v_mov_b64_e32 v[58:59], 0
	v_mov_b64_e32 v[60:61], 0
	v_mov_b64_e32 v[62:63], 0
	v_mov_b64_e32 v[64:65], 0
	v_mov_b64_e32 v[66:67], 0
	v_mov_b64_e32 v[68:69], 0
	v_mov_b64_e32 v[70:71], 0
	v_mov_b64_e32 v[72:73], 0
	v_mov_b64_e32 v[74:75], 0
	v_mov_b64_e32 v[80:81], 0
	v_mov_b64_e32 v[82:83], 0
	v_mov_b64_e32 v[88:89], 0
	v_mov_b64_e32 v[90:91], 0
	v_mov_b64_e32 v[96:97], 0
	v_mov_b64_e32 v[98:99], 0
	v_mov_b64_e32 v[104:105], 0
	v_mov_b64_e32 v[106:107], 0
	v_mov_b64_e32 v[116:117], 0
	v_mov_b64_e32 v[118:119], 0
	v_mov_b64_e32 v[76:77], 0
	v_mov_b64_e32 v[78:79], 0
	v_mov_b64_e32 v[84:85], 0
	v_mov_b64_e32 v[86:87], 0
	v_mov_b64_e32 v[92:93], 0
	v_mov_b64_e32 v[94:95], 0
	v_mov_b64_e32 v[100:101], 0
	v_mov_b64_e32 v[102:103], 0
	v_mov_b64_e32 v[108:109], 0
	v_mov_b64_e32 v[110:111], 0
	v_mov_b64_e32 v[112:113], 0
	v_mov_b64_e32 v[114:115], 0
	v_mov_b64_e32 v[120:121], 0
	v_mov_b64_e32 v[122:123], 0
	v_mov_b64_e32 v[124:125], 0
	v_mov_b64_e32 v[126:127], 0

; template <class Desc, class Epi>
; DI void gemm_phase(LAS unsigned char* lds, const Desc& D, const Epi& E, int wv) {
;     ...
; #pragma unroll
;         for (int a = 0; a < 2; ++a)
; #pragma unroll
;             for (int b = 0; b < 2; ++b)
; #pragma unroll
;                 for (int m = 0; m < 4; ++m)
; #pragma unroll
;                     for (int n = 0; n < 2; ++n) acc[a][b][m][n] = (f32x4){0.f, 0.f, 0.f, 0.f};
;         cur = nxt; cA = nA; cB = nB; ++ui;
.LBB0_961:
	s_add_u32 s70, s70, 0x80080
	s_addc_u32 s71, s71, 0
	s_add_u32 s9, s72, 0x100
	v_mov_b32_e32 v0, 0
	v_cmp_lt_i64_e64 s[4:5], s[4:5], v[142:143]
	s_addc_u32 s10, s73, 0
	s_mov_b32 s53, -2
	v_mov_b32_e32 v1, v0
	v_mov_b64_e32 v[2:3], 0
	v_mov_b64_e32 v[4:5], 0
	v_mov_b64_e32 v[6:7], 0
	v_mov_b64_e32 v[16:17], 0
	v_mov_b64_e32 v[18:19], 0
	v_mov_b64_e32 v[20:21], 0
	v_mov_b64_e32 v[22:23], 0
	v_mov_b64_e32 v[32:33], 0
	v_mov_b64_e32 v[34:35], 0
	v_mov_b64_e32 v[36:37], 0
	v_mov_b64_e32 v[38:39], 0
	v_mov_b64_e32 v[48:49], 0
	v_mov_b64_e32 v[50:51], 0
	v_mov_b64_e32 v[52:53], 0
	v_mov_b64_e32 v[54:55], 0
	v_mov_b64_e32 v[8:9], 0
	v_mov_b64_e32 v[10:11], 0
	v_mov_b64_e32 v[12:13], 0
	v_mov_b64_e32 v[14:15], 0
	v_mov_b64_e32 v[24:25], 0
	v_mov_b64_e32 v[26:27], 0
	v_mov_b64_e32 v[28:29], 0
	v_mov_b64_e32 v[30:31], 0
	v_mov_b64_e32 v[40:41], 0
	v_mov_b64_e32 v[42:43], 0
	v_mov_b64_e32 v[44:45], 0
	v_mov_b64_e32 v[46:47], 0
	v_mov_b64_e32 v[56:57], 0
	v_mov_b64_e32 v[58:59], 0
	v_mov_b64_e32 v[60:61], 0
	v_mov_b64_e32 v[62:63], 0
	v_mov_b64_e32 v[64:65], 0
	v_mov_b64_e32 v[66:67], 0
	v_mov_b64_e32 v[68:69], 0
	v_mov_b64_e32 v[70:71], 0
	v_mov_b64_e32 v[80:81], 0
	v_mov_b64_e32 v[82:83], 0
	v_mov_b64_e32 v[84:85], 0
	v_mov_b64_e32 v[86:87], 0
	v_mov_b64_e32 v[96:97], 0
	v_mov_b64_e32 v[98:99], 0
	v_mov_b64_e32 v[100:101], 0
	v_mov_b64_e32 v[102:103], 0
	v_mov_b64_e32 v[112:113], 0
	v_mov_b64_e32 v[114:115], 0
	v_mov_b64_e32 v[116:117], 0
	v_mov_b64_e32 v[118:119], 0
	v_mov_b64_e32 v[72:73], 0
	v_mov_b64_e32 v[74:75], 0
	v_mov_b64_e32 v[76:77], 0
	v_mov_b64_e32 v[78:79], 0
	v_mov_b64_e32 v[88:89], 0
	v_mov_b64_e32 v[90:91], 0
	v_mov_b64_e32 v[92:93], 0
	v_mov_b64_e32 v[94:95], 0
	v_mov_b64_e32 v[104:105], 0
	v_mov_b64_e32 v[106:107], 0
	v_mov_b64_e32 v[108:109], 0
	v_mov_b64_e32 v[110:111], 0
	v_mov_b64_e32 v[120:121], 0
	v_mov_b64_e32 v[122:123], 0
	v_mov_b64_e32 v[124:125], 0
	v_mov_b64_e32 v[126:127], 0
	s_mov_b64 s[16:17], s[96:97]

; template <class Desc, class Epi>
; DI void gemm_phase(LAS unsigned char* lds, const Desc& D, const Epi& E, int wv) {
;     ...
; #pragma unroll
;         for (int a = 0; a < 2; ++a)
; #pragma unroll
;             for (int b = 0; b < 2; ++b)
; #pragma unroll
;                 for (int m = 0; m < 4; ++m)
; #pragma unroll
;                     for (int n = 0; n < 2; ++n) acc[a][b][m][n] = (f32x4){0.f, 0.f, 0.f, 0.f};
;         cur = nxt; cA = nA; cB = nB; ++ui;
.LBB0_1312:
	s_add_u32 s22, s22, 0x80080
	s_addc_u32 s23, s23, 0
	s_add_u32 s19, s40, 0x100
	v_mov_b32_e32 v0, 0
	v_cmp_lt_i64_e64 s[4:5], s[4:5], v[142:143]
	s_addc_u32 s21, s41, 0
	s_mov_b32 s50, -2
	v_mov_b32_e32 v1, v0
	v_mov_b64_e32 v[2:3], 0
	v_mov_b64_e32 v[4:5], 0
	v_mov_b64_e32 v[6:7], 0
	v_mov_b64_e32 v[16:17], 0
	v_mov_b64_e32 v[18:19], 0
	v_mov_b64_e32 v[20:21], 0
	v_mov_b64_e32 v[22:23], 0
	v_mov_b64_e32 v[32:33], 0
	v_mov_b64_e32 v[34:35], 0
	v_mov_b64_e32 v[36:37], 0
	v_mov_b64_e32 v[38:39], 0
	v_mov_b64_e32 v[48:49], 0
	v_mov_b64_e32 v[50:51], 0
	v_mov_b64_e32 v[52:53], 0
	v_mov_b64_e32 v[54:55], 0
	v_mov_b64_e32 v[8:9], 0
	v_mov_b64_e32 v[10:11], 0
	v_mov_b64_e32 v[12:13], 0
	v_mov_b64_e32 v[14:15], 0
	v_mov_b64_e32 v[24:25], 0
	v_mov_b64_e32 v[26:27], 0
	v_mov_b64_e32 v[28:29], 0
	v_mov_b64_e32 v[30:31], 0
	v_mov_b64_e32 v[40:41], 0
	v_mov_b64_e32 v[42:43], 0
	v_mov_b64_e32 v[44:45], 0
	v_mov_b64_e32 v[46:47], 0
	v_mov_b64_e32 v[56:57], 0
	v_mov_b64_e32 v[58:59], 0
	v_mov_b64_e32 v[60:61], 0
	v_mov_b64_e32 v[62:63], 0
	v_mov_b64_e32 v[64:65], 0
	v_mov_b64_e32 v[66:67], 0
	v_mov_b64_e32 v[68:69], 0
	v_mov_b64_e32 v[70:71], 0
	v_mov_b64_e32 v[80:81], 0
	v_mov_b64_e32 v[82:83], 0
	v_mov_b64_e32 v[84:85], 0
	v_mov_b64_e32 v[86:87], 0
	v_mov_b64_e32 v[96:97], 0
	v_mov_b64_e32 v[98:99], 0
	v_mov_b64_e32 v[100:101], 0
	v_mov_b64_e32 v[102:103], 0
	v_mov_b64_e32 v[112:113], 0
	v_mov_b64_e32 v[114:115], 0
	v_mov_b64_e32 v[116:117], 0
	v_mov_b64_e32 v[118:119], 0
	v_mov_b64_e32 v[72:73], 0
	v_mov_b64_e32 v[74:75], 0
	v_mov_b64_e32 v[76:77], 0
	v_mov_b64_e32 v[78:79], 0
	v_mov_b64_e32 v[88:89], 0
	v_mov_b64_e32 v[90:91], 0
	v_mov_b64_e32 v[92:93], 0
	v_mov_b64_e32 v[94:95], 0
	v_mov_b64_e32 v[104:105], 0
	v_mov_b64_e32 v[106:107], 0
	v_mov_b64_e32 v[108:109], 0
	v_mov_b64_e32 v[110:111], 0
	v_mov_b64_e32 v[120:121], 0
	v_mov_b64_e32 v[122:123], 0
	v_mov_b64_e32 v[124:125], 0
	v_mov_b64_e32 v[126:127], 0

; template <class Desc, class Epi>
; DI void gemm_phase(LAS unsigned char* lds, const Desc& D, const Epi& E, int wv) {
;     ...
; #pragma unroll
;         for (int a = 0; a < 2; ++a)
; #pragma unroll
;             for (int b = 0; b < 2; ++b)
; #pragma unroll
;                 for (int m = 0; m < 4; ++m)
; #pragma unroll
;                     for (int n = 0; n < 2; ++n) acc[a][b][m][n] = (f32x4){0.f, 0.f, 0.f, 0.f};
;         cur = nxt; cA = nA; cB = nB; ++ui;
.LBB0_1500:
	s_add_u32 s20, s20, 0x80080
	s_addc_u32 s21, s21, 0
	s_add_u32 s15, s22, 0x100
	v_mov_b32_e32 v0, 0
	s_addc_u32 s17, s23, 0
	s_mov_b32 s64, -2
	v_mov_b32_e32 v1, v0
	v_mov_b64_e32 v[2:3], 0
	v_mov_b64_e32 v[4:5], 0
	v_mov_b64_e32 v[6:7], 0
	v_mov_b64_e32 v[12:13], 0
	v_mov_b64_e32 v[14:15], 0
	v_mov_b64_e32 v[20:21], 0
	v_mov_b64_e32 v[22:23], 0
	v_mov_b64_e32 v[28:29], 0
	v_mov_b64_e32 v[30:31], 0
	v_mov_b64_e32 v[36:37], 0
	v_mov_b64_e32 v[38:39], 0
	v_mov_b64_e32 v[44:45], 0
	v_mov_b64_e32 v[46:47], 0
	v_mov_b64_e32 v[52:53], 0
	v_mov_b64_e32 v[54:55], 0
	v_mov_b64_e32 v[8:9], 0
	v_mov_b64_e32 v[10:11], 0
	v_mov_b64_e32 v[16:17], 0
	v_mov_b64_e32 v[18:19], 0
	v_mov_b64_e32 v[24:25], 0
	v_mov_b64_e32 v[26:27], 0
	v_mov_b64_e32 v[32:33], 0
	v_mov_b64_e32 v[34:35], 0
	v_mov_b64_e32 v[40:41], 0
	v_mov_b64_e32 v[42:43], 0
	v_mov_b64_e32 v[48:49], 0
	v_mov_b64_e32 v[50:51], 0
	v_mov_b64_e32 v[56:57], 0
	v_mov_b64_e32 v[58:59], 0
	v_mov_b64_e32 v[60:61], 0
	v_mov_b64_e32 v[62:63], 0
	v_mov_b64_e32 v[64:65], 0
	v_mov_b64_e32 v[66:67], 0
	v_mov_b64_e32 v[68:69], 0
	v_mov_b64_e32 v[70:71], 0
	v_mov_b64_e32 v[76:77], 0
	v_mov_b64_e32 v[78:79], 0
	v_mov_b64_e32 v[84:85], 0
	v_mov_b64_e32 v[86:87], 0
	v_mov_b64_e32 v[92:93], 0
	v_mov_b64_e32 v[94:95], 0
	v_mov_b64_e32 v[100:101], 0
	v_mov_b64_e32 v[102:103], 0
	v_mov_b64_e32 v[108:109], 0
	v_mov_b64_e32 v[110:111], 0
	v_mov_b64_e32 v[116:117], 0
	v_mov_b64_e32 v[118:119], 0
	v_mov_b64_e32 v[72:73], 0
	v_mov_b64_e32 v[74:75], 0
	v_mov_b64_e32 v[80:81], 0
	v_mov_b64_e32 v[82:83], 0
	v_mov_b64_e32 v[88:89], 0
	v_mov_b64_e32 v[90:91], 0
	v_mov_b64_e32 v[96:97], 0
	v_mov_b64_e32 v[98:99], 0
	v_mov_b64_e32 v[104:105], 0
	v_mov_b64_e32 v[106:107], 0
	v_mov_b64_e32 v[112:113], 0
	v_mov_b64_e32 v[114:115], 0
	v_mov_b64_e32 v[120:121], 0
	v_mov_b64_e32 v[122:123], 0
	v_mov_b64_e32 v[124:125], 0
	v_mov_b64_e32 v[126:127], 0

; template <class Desc, class Epi>
; DI void gemm_phase(LAS unsigned char* lds, const Desc& D, const Epi& E, int wv) {
;     ...
; #pragma unroll
;         for (int a = 0; a < 2; ++a)
; #pragma unroll
;             for (int b = 0; b < 2; ++b)
; #pragma unroll
;                 for (int m = 0; m < 4; ++m)
; #pragma unroll
;                     for (int n = 0; n < 2; ++n) acc[a][b][m][n] = (f32x4){0.f, 0.f, 0.f, 0.f};
;         cur = nxt; cA = nA; cB = nB; ++ui;
.LBB0_1631:
	s_add_u32 s62, s62, 0x80080
	s_addc_u32 s63, s63, 0
	s_add_u32 s5, s64, 0x100
	v_mov_b32_e32 v0, 0
	v_cmp_lt_i64_e64 s[0:1], s[0:1], v[142:143]
	s_addc_u32 s7, s65, 0
	s_mov_b32 s8, -2
	v_mov_b32_e32 v1, v0
	v_mov_b64_e32 v[2:3], 0
	v_mov_b64_e32 v[4:5], 0
	v_mov_b64_e32 v[6:7], 0
	v_mov_b64_e32 v[16:17], 0
	v_mov_b64_e32 v[18:19], 0
	v_mov_b64_e32 v[20:21], 0
	v_mov_b64_e32 v[22:23], 0
	v_mov_b64_e32 v[32:33], 0
	v_mov_b64_e32 v[34:35], 0
	v_mov_b64_e32 v[36:37], 0
	v_mov_b64_e32 v[38:39], 0
	v_mov_b64_e32 v[48:49], 0
	v_mov_b64_e32 v[50:51], 0
	v_mov_b64_e32 v[52:53], 0
	v_mov_b64_e32 v[54:55], 0
	v_mov_b64_e32 v[8:9], 0
	v_mov_b64_e32 v[10:11], 0
	v_mov_b64_e32 v[12:13], 0
	v_mov_b64_e32 v[14:15], 0
	v_mov_b64_e32 v[24:25], 0
	v_mov_b64_e32 v[26:27], 0
	v_mov_b64_e32 v[28:29], 0
	v_mov_b64_e32 v[30:31], 0
	v_mov_b64_e32 v[40:41], 0
	v_mov_b64_e32 v[42:43], 0
	v_mov_b64_e32 v[44:45], 0
	v_mov_b64_e32 v[46:47], 0
	v_mov_b64_e32 v[56:57], 0
	v_mov_b64_e32 v[58:59], 0
	v_mov_b64_e32 v[60:61], 0
	v_mov_b64_e32 v[62:63], 0
	v_mov_b64_e32 v[64:65], 0
	v_mov_b64_e32 v[66:67], 0
	v_mov_b64_e32 v[68:69], 0
	v_mov_b64_e32 v[70:71], 0
	v_mov_b64_e32 v[80:81], 0
	v_mov_b64_e32 v[82:83], 0
	v_mov_b64_e32 v[84:85], 0
	v_mov_b64_e32 v[86:87], 0
	v_mov_b64_e32 v[96:97], 0
	v_mov_b64_e32 v[98:99], 0
	v_mov_b64_e32 v[100:101], 0
	v_mov_b64_e32 v[102:103], 0
	v_mov_b64_e32 v[112:113], 0
	v_mov_b64_e32 v[114:115], 0
	v_mov_b64_e32 v[116:117], 0
	v_mov_b64_e32 v[118:119], 0
	v_mov_b64_e32 v[72:73], 0
	v_mov_b64_e32 v[74:75], 0
	v_mov_b64_e32 v[76:77], 0
	v_mov_b64_e32 v[78:79], 0
	v_mov_b64_e32 v[88:89], 0
	v_mov_b64_e32 v[90:91], 0
	v_mov_b64_e32 v[92:93], 0
	v_mov_b64_e32 v[94:95], 0
	v_mov_b64_e32 v[104:105], 0
	v_mov_b64_e32 v[106:107], 0
	v_mov_b64_e32 v[108:109], 0
	v_mov_b64_e32 v[110:111], 0
	v_mov_b64_e32 v[120:121], 0
	v_mov_b64_e32 v[122:123], 0
	v_mov_b64_e32 v[124:125], 0
	v_mov_b64_e32 v[126:127], 0

; template <class Desc, class Epi>
; DI void gemm_phase(LAS unsigned char* lds, const Desc& D, const Epi& E, int wv) {
;     ...
; #pragma unroll
;         for (int a = 0; a < 2; ++a)
; #pragma unroll
;             for (int b = 0; b < 2; ++b)
; #pragma unroll
;                 for (int m = 0; m < 4; ++m)
; #pragma unroll
;                     for (int n = 0; n < 2; ++n) acc[a][b][m][n] = (f32x4){0.f, 0.f, 0.f, 0.f};
;         cur = nxt; cA = nA; cB = nB; ++ui;
.LBB0_2087:
	s_add_u32 s40, s40, 0x80080
	s_addc_u32 s41, s41, 0
	s_add_u32 s19, s42, 0x100
	v_mov_b32_e32 v0, 0
	s_addc_u32 s21, s43, 0
	s_mov_b32 s66, -2
	v_mov_b32_e32 v1, v0
	v_mov_b64_e32 v[2:3], 0
	v_mov_b64_e32 v[4:5], 0
	v_mov_b64_e32 v[6:7], 0
	v_mov_b64_e32 v[12:13], 0
	v_mov_b64_e32 v[14:15], 0
	v_mov_b64_e32 v[20:21], 0
	v_mov_b64_e32 v[22:23], 0
	v_mov_b64_e32 v[28:29], 0
	v_mov_b64_e32 v[30:31], 0
	v_mov_b64_e32 v[36:37], 0
	v_mov_b64_e32 v[38:39], 0
	v_mov_b64_e32 v[44:45], 0
	v_mov_b64_e32 v[46:47], 0
	v_mov_b64_e32 v[52:53], 0
	v_mov_b64_e32 v[54:55], 0
	v_mov_b64_e32 v[8:9], 0
	v_mov_b64_e32 v[10:11], 0
	v_mov_b64_e32 v[16:17], 0
	v_mov_b64_e32 v[18:19], 0
	v_mov_b64_e32 v[24:25], 0
	v_mov_b64_e32 v[26:27], 0
	v_mov_b64_e32 v[32:33], 0
	v_mov_b64_e32 v[34:35], 0
	v_mov_b64_e32 v[40:41], 0
	v_mov_b64_e32 v[42:43], 0
	v_mov_b64_e32 v[48:49], 0
	v_mov_b64_e32 v[50:51], 0
	v_mov_b64_e32 v[56:57], 0
	v_mov_b64_e32 v[58:59], 0
	v_mov_b64_e32 v[60:61], 0
	v_mov_b64_e32 v[62:63], 0
	v_mov_b64_e32 v[64:65], 0
	v_mov_b64_e32 v[66:67], 0
	v_mov_b64_e32 v[68:69], 0
	v_mov_b64_e32 v[70:71], 0
	v_mov_b64_e32 v[76:77], 0
	v_mov_b64_e32 v[78:79], 0
	v_mov_b64_e32 v[84:85], 0
	v_mov_b64_e32 v[86:87], 0
	v_mov_b64_e32 v[92:93], 0
	v_mov_b64_e32 v[94:95], 0
	v_mov_b64_e32 v[100:101], 0
	v_mov_b64_e32 v[102:103], 0
	v_mov_b64_e32 v[108:109], 0
	v_mov_b64_e32 v[110:111], 0
	v_mov_b64_e32 v[116:117], 0
	v_mov_b64_e32 v[118:119], 0
	v_mov_b64_e32 v[72:73], 0
	v_mov_b64_e32 v[74:75], 0
	v_mov_b64_e32 v[80:81], 0
	v_mov_b64_e32 v[82:83], 0
	v_mov_b64_e32 v[88:89], 0
	v_mov_b64_e32 v[90:91], 0
	v_mov_b64_e32 v[96:97], 0
	v_mov_b64_e32 v[98:99], 0
	v_mov_b64_e32 v[104:105], 0
	v_mov_b64_e32 v[106:107], 0
	v_mov_b64_e32 v[112:113], 0
	v_mov_b64_e32 v[114:115], 0
	v_mov_b64_e32 v[120:121], 0
	v_mov_b64_e32 v[122:123], 0
	v_mov_b64_e32 v[124:125], 0
	v_mov_b64_e32 v[126:127], 0

; template <class Desc, class Epi>
; DI void gemm_phase(LAS unsigned char* lds, const Desc& D, const Epi& E, int wv) {
;     ...
; #pragma unroll
;         for (int a = 0; a < 2; ++a)
; #pragma unroll
;             for (int b = 0; b < 2; ++b)
; #pragma unroll
;                 for (int m = 0; m < 4; ++m)
; #pragma unroll
;                     for (int n = 0; n < 2; ++n) acc[a][b][m][n] = (f32x4){0.f, 0.f, 0.f, 0.f};
;         cur = nxt; cA = nA; cB = nB; ++ui;
.LBB0_2212:
	s_add_u32 s42, s42, 0x80080
	s_addc_u32 s43, s43, 0
	s_add_u32 s23, s48, 0x100
	v_mov_b32_e32 v0, 0
	s_addc_u32 s25, s49, 0
	s_mov_b32 s41, -2
	v_mov_b32_e32 v1, v0
	v_mov_b64_e32 v[2:3], 0
	v_mov_b64_e32 v[4:5], 0
	v_mov_b64_e32 v[6:7], 0
	v_mov_b64_e32 v[16:17], 0
	v_mov_b64_e32 v[18:19], 0
	v_mov_b64_e32 v[20:21], 0
	v_mov_b64_e32 v[22:23], 0
	v_mov_b64_e32 v[32:33], 0
	v_mov_b64_e32 v[34:35], 0
	v_mov_b64_e32 v[36:37], 0
	v_mov_b64_e32 v[38:39], 0
	v_mov_b64_e32 v[48:49], 0
	v_mov_b64_e32 v[50:51], 0
	v_mov_b64_e32 v[52:53], 0
	v_mov_b64_e32 v[54:55], 0
	v_mov_b64_e32 v[8:9], 0
	v_mov_b64_e32 v[10:11], 0
	v_mov_b64_e32 v[12:13], 0
	v_mov_b64_e32 v[14:15], 0
	v_mov_b64_e32 v[24:25], 0
	v_mov_b64_e32 v[26:27], 0
	v_mov_b64_e32 v[28:29], 0
	v_mov_b64_e32 v[30:31], 0
	v_mov_b64_e32 v[40:41], 0
	v_mov_b64_e32 v[42:43], 0
	v_mov_b64_e32 v[44:45], 0
	v_mov_b64_e32 v[46:47], 0
	v_mov_b64_e32 v[56:57], 0
	v_mov_b64_e32 v[58:59], 0
	v_mov_b64_e32 v[60:61], 0
	v_mov_b64_e32 v[62:63], 0
	v_mov_b64_e32 v[64:65], 0
	v_mov_b64_e32 v[66:67], 0
	v_mov_b64_e32 v[68:69], 0
	v_mov_b64_e32 v[70:71], 0
	v_mov_b64_e32 v[80:81], 0
	v_mov_b64_e32 v[82:83], 0
	v_mov_b64_e32 v[84:85], 0
	v_mov_b64_e32 v[86:87], 0
	v_mov_b64_e32 v[96:97], 0
	v_mov_b64_e32 v[98:99], 0
	v_mov_b64_e32 v[100:101], 0
	v_mov_b64_e32 v[102:103], 0
	v_mov_b64_e32 v[112:113], 0
	v_mov_b64_e32 v[114:115], 0
	v_mov_b64_e32 v[116:117], 0
	v_mov_b64_e32 v[118:119], 0
	v_mov_b64_e32 v[72:73], 0
	v_mov_b64_e32 v[74:75], 0
	v_mov_b64_e32 v[76:77], 0
	v_mov_b64_e32 v[78:79], 0
	v_mov_b64_e32 v[88:89], 0
	v_mov_b64_e32 v[90:91], 0
	v_mov_b64_e32 v[92:93], 0
	v_mov_b64_e32 v[94:95], 0
	v_mov_b64_e32 v[104:105], 0
	v_mov_b64_e32 v[106:107], 0
	v_mov_b64_e32 v[108:109], 0
	v_mov_b64_e32 v[110:111], 0
	v_mov_b64_e32 v[120:121], 0
	v_mov_b64_e32 v[122:123], 0
	v_mov_b64_e32 v[124:125], 0
	v_mov_b64_e32 v[126:127], 0

; template <class Desc, class Epi>
; DI void gemm_phase(LAS unsigned char* lds, const Desc& D, const Epi& E, int wv) {
;     ...
; #pragma unroll
;         for (int a = 0; a < 2; ++a)
; #pragma unroll
;             for (int b = 0; b < 2; ++b)
; #pragma unroll
;                 for (int m = 0; m < 4; ++m)
; #pragma unroll
;                     for (int n = 0; n < 2; ++n) acc[a][b][m][n] = (f32x4){0.f, 0.f, 0.f, 0.f};
;         cur = nxt; cA = nA; cB = nB; ++ui;
.LBB0_2238:
	s_add_u32 s6, s6, 0x20080
	s_addc_u32 s7, s7, 0
	s_add_u32 s48, s8, 0x100
	v_mov_b32_e32 v0, 0
	s_addc_u32 s49, s9, 0
	s_mov_b32 s50, -2
	v_mov_b32_e32 v1, v0
	v_mov_b64_e32 v[2:3], 0
	v_mov_b64_e32 v[4:5], 0
	v_mov_b64_e32 v[6:7], 0
	v_mov_b64_e32 v[16:17], 0
	v_mov_b64_e32 v[18:19], 0
	v_mov_b64_e32 v[20:21], 0
	v_mov_b64_e32 v[22:23], 0
	v_mov_b64_e32 v[32:33], 0
	v_mov_b64_e32 v[34:35], 0
	v_mov_b64_e32 v[36:37], 0
	v_mov_b64_e32 v[38:39], 0
	v_mov_b64_e32 v[48:49], 0
	v_mov_b64_e32 v[50:51], 0
	v_mov_b64_e32 v[52:53], 0
	v_mov_b64_e32 v[54:55], 0
	v_mov_b64_e32 v[8:9], 0
	v_mov_b64_e32 v[10:11], 0
	v_mov_b64_e32 v[12:13], 0
	v_mov_b64_e32 v[14:15], 0
	v_mov_b64_e32 v[24:25], 0
	v_mov_b64_e32 v[26:27], 0
	v_mov_b64_e32 v[28:29], 0
	v_mov_b64_e32 v[30:31], 0
	v_mov_b64_e32 v[40:41], 0
	v_mov_b64_e32 v[42:43], 0
	v_mov_b64_e32 v[44:45], 0
	v_mov_b64_e32 v[46:47], 0
	v_mov_b64_e32 v[56:57], 0
	v_mov_b64_e32 v[58:59], 0
	v_mov_b64_e32 v[60:61], 0
	v_mov_b64_e32 v[62:63], 0
	v_mov_b64_e32 v[64:65], 0
	v_mov_b64_e32 v[66:67], 0
	v_mov_b64_e32 v[68:69], 0
	v_mov_b64_e32 v[70:71], 0
	v_mov_b64_e32 v[80:81], 0
	v_mov_b64_e32 v[82:83], 0
	v_mov_b64_e32 v[84:85], 0
	v_mov_b64_e32 v[86:87], 0
	v_mov_b64_e32 v[96:97], 0
	v_mov_b64_e32 v[98:99], 0
	v_mov_b64_e32 v[100:101], 0
	v_mov_b64_e32 v[102:103], 0
	v_mov_b64_e32 v[112:113], 0
	v_mov_b64_e32 v[114:115], 0
	v_mov_b64_e32 v[116:117], 0
	v_mov_b64_e32 v[118:119], 0
	v_mov_b64_e32 v[72:73], 0
	v_mov_b64_e32 v[74:75], 0
	v_mov_b64_e32 v[76:77], 0
	v_mov_b64_e32 v[78:79], 0
	v_mov_b64_e32 v[88:89], 0
	v_mov_b64_e32 v[90:91], 0
	v_mov_b64_e32 v[92:93], 0
	v_mov_b64_e32 v[94:95], 0
	v_mov_b64_e32 v[104:105], 0
	v_mov_b64_e32 v[106:107], 0
	v_mov_b64_e32 v[108:109], 0
	v_mov_b64_e32 v[110:111], 0
	v_mov_b64_e32 v[120:121], 0
	v_mov_b64_e32 v[122:123], 0
	v_mov_b64_e32 v[124:125], 0
	v_mov_b64_e32 v[126:127], 0

; template <class Desc, class Epi>
; DI void gemm_phase(LAS unsigned char* lds, const Desc& D, const Epi& E, int wv) {
;     ...
; #pragma unroll
;         for (int a = 0; a < 2; ++a)
; #pragma unroll
;             for (int b = 0; b < 2; ++b)
; #pragma unroll
;                 for (int m = 0; m < 4; ++m)
; #pragma unroll
;                     for (int n = 0; n < 2; ++n) acc[a][b][m][n] = (f32x4){0.f, 0.f, 0.f, 0.f};
;         cur = nxt; cA = nA; cB = nB; ++ui;
.LBB0_2479:
	s_add_u32 s40, s40, 0x100080
	s_addc_u32 s41, s41, 0
	s_add_u32 s5, s42, 0x100
	v_mov_b32_e32 v0, 0
	s_addc_u32 s23, s43, 0
	s_mov_b32 s48, -2
	v_mov_b32_e32 v1, v0
	v_mov_b64_e32 v[2:3], 0
	v_mov_b64_e32 v[4:5], 0
	v_mov_b64_e32 v[6:7], 0
	v_mov_b64_e32 v[16:17], 0
	v_mov_b64_e32 v[18:19], 0
	v_mov_b64_e32 v[20:21], 0
	v_mov_b64_e32 v[22:23], 0
	v_mov_b64_e32 v[32:33], 0
	v_mov_b64_e32 v[34:35], 0
	v_mov_b64_e32 v[36:37], 0
	v_mov_b64_e32 v[38:39], 0
	v_mov_b64_e32 v[48:49], 0
	v_mov_b64_e32 v[50:51], 0
	v_mov_b64_e32 v[52:53], 0
	v_mov_b64_e32 v[54:55], 0
	v_mov_b64_e32 v[8:9], 0
	v_mov_b64_e32 v[10:11], 0
	v_mov_b64_e32 v[12:13], 0
	v_mov_b64_e32 v[14:15], 0
	v_mov_b64_e32 v[24:25], 0
	v_mov_b64_e32 v[26:27], 0
	v_mov_b64_e32 v[28:29], 0
	v_mov_b64_e32 v[30:31], 0
	v_mov_b64_e32 v[40:41], 0
	v_mov_b64_e32 v[42:43], 0
	v_mov_b64_e32 v[44:45], 0
	v_mov_b64_e32 v[46:47], 0
	v_mov_b64_e32 v[56:57], 0
	v_mov_b64_e32 v[58:59], 0
	v_mov_b64_e32 v[60:61], 0
	v_mov_b64_e32 v[62:63], 0
	v_mov_b64_e32 v[64:65], 0
	v_mov_b64_e32 v[66:67], 0
	v_mov_b64_e32 v[68:69], 0
	v_mov_b64_e32 v[70:71], 0
	v_mov_b64_e32 v[80:81], 0
	v_mov_b64_e32 v[82:83], 0
	v_mov_b64_e32 v[84:85], 0
	v_mov_b64_e32 v[86:87], 0
	v_mov_b64_e32 v[96:97], 0
	v_mov_b64_e32 v[98:99], 0
	v_mov_b64_e32 v[100:101], 0
	v_mov_b64_e32 v[102:103], 0
	v_mov_b64_e32 v[112:113], 0
	v_mov_b64_e32 v[114:115], 0
	v_mov_b64_e32 v[116:117], 0
	v_mov_b64_e32 v[118:119], 0
	v_mov_b64_e32 v[72:73], 0
	v_mov_b64_e32 v[74:75], 0
	v_mov_b64_e32 v[76:77], 0
	v_mov_b64_e32 v[78:79], 0
	v_mov_b64_e32 v[88:89], 0
	v_mov_b64_e32 v[90:91], 0
	v_mov_b64_e32 v[92:93], 0
	v_mov_b64_e32 v[94:95], 0
	v_mov_b64_e32 v[104:105], 0
	v_mov_b64_e32 v[106:107], 0
	v_mov_b64_e32 v[108:109], 0
	v_mov_b64_e32 v[110:111], 0
	v_mov_b64_e32 v[120:121], 0
	v_mov_b64_e32 v[122:123], 0
	v_mov_b64_e32 v[124:125], 0
	v_mov_b64_e32 v[126:127], 0

; template <class Desc, class Epi>
; DI void gemm_phase(LAS unsigned char* lds, const Desc& D, const Epi& E, int wv) {
;     ...
; #pragma unroll
;         for (int a = 0; a < 2; ++a)
; #pragma unroll
;             for (int b = 0; b < 2; ++b)
; #pragma unroll
;                 for (int m = 0; m < 4; ++m)
; #pragma unroll
;                     for (int n = 0; n < 2; ++n) acc[a][b][m][n] = (f32x4){0.f, 0.f, 0.f, 0.f};
;         cur = nxt; cA = nA; cB = nB; ++ui;
.LBB0_2705:
	s_add_u32 s24, s24, 0x80080
	s_addc_u32 s25, s25, 0
	s_add_u32 s19, s34, 0x100
	v_mov_b32_e32 v0, 0
	s_addc_u32 s21, s35, 0
	s_mov_b32 s66, -2
	v_mov_b32_e32 v1, v0
	v_mov_b64_e32 v[2:3], 0
	v_mov_b64_e32 v[4:5], 0
	v_mov_b64_e32 v[6:7], 0
	v_mov_b64_e32 v[12:13], 0
	v_mov_b64_e32 v[14:15], 0
	v_mov_b64_e32 v[20:21], 0
	v_mov_b64_e32 v[22:23], 0
	v_mov_b64_e32 v[28:29], 0
	v_mov_b64_e32 v[30:31], 0
	v_mov_b64_e32 v[36:37], 0
	v_mov_b64_e32 v[38:39], 0
	v_mov_b64_e32 v[44:45], 0
	v_mov_b64_e32 v[46:47], 0
	v_mov_b64_e32 v[52:53], 0
	v_mov_b64_e32 v[54:55], 0
	v_mov_b64_e32 v[8:9], 0
	v_mov_b64_e32 v[10:11], 0
	v_mov_b64_e32 v[16:17], 0
	v_mov_b64_e32 v[18:19], 0
	v_mov_b64_e32 v[24:25], 0
	v_mov_b64_e32 v[26:27], 0
	v_mov_b64_e32 v[32:33], 0
	v_mov_b64_e32 v[34:35], 0
	v_mov_b64_e32 v[40:41], 0
	v_mov_b64_e32 v[42:43], 0
	v_mov_b64_e32 v[48:49], 0
	v_mov_b64_e32 v[50:51], 0
	v_mov_b64_e32 v[56:57], 0
	v_mov_b64_e32 v[58:59], 0
	v_mov_b64_e32 v[60:61], 0
	v_mov_b64_e32 v[62:63], 0
	v_mov_b64_e32 v[64:65], 0
	v_mov_b64_e32 v[66:67], 0
	v_mov_b64_e32 v[68:69], 0
	v_mov_b64_e32 v[70:71], 0
	v_mov_b64_e32 v[76:77], 0
	v_mov_b64_e32 v[78:79], 0
	v_mov_b64_e32 v[84:85], 0
	v_mov_b64_e32 v[86:87], 0
	v_mov_b64_e32 v[92:93], 0
	v_mov_b64_e32 v[94:95], 0
	v_mov_b64_e32 v[100:101], 0
	v_mov_b64_e32 v[102:103], 0
	v_mov_b64_e32 v[108:109], 0
	v_mov_b64_e32 v[110:111], 0
	v_mov_b64_e32 v[116:117], 0
	v_mov_b64_e32 v[118:119], 0
	v_mov_b64_e32 v[72:73], 0
	v_mov_b64_e32 v[74:75], 0
	v_mov_b64_e32 v[80:81], 0
	v_mov_b64_e32 v[82:83], 0
	v_mov_b64_e32 v[88:89], 0
	v_mov_b64_e32 v[90:91], 0
	v_mov_b64_e32 v[96:97], 0
	v_mov_b64_e32 v[98:99], 0
	v_mov_b64_e32 v[104:105], 0
	v_mov_b64_e32 v[106:107], 0
	v_mov_b64_e32 v[112:113], 0
	v_mov_b64_e32 v[114:115], 0
	v_mov_b64_e32 v[120:121], 0
	v_mov_b64_e32 v[122:123], 0
	v_mov_b64_e32 v[124:125], 0
	v_mov_b64_e32 v[126:127], 0
